# LayerNorm layer 0: next-layer shift/scale loads hoisted above the stores (they were issued between stores, each followed by vmcnt(0))
# speedup vs baseline: 1.0243x; 1.0087x over previous
; DI void phase_ln(const P& p, int l) {
;     ...
;       const int mr = rr < MLAT ? (rr >> 11) : 16;
;       const float* md = p.mod + (size_t)(1 * 17 + mr) * 3072;
; #pragma unroll
;       for (int i = 0; i < 4; ++i) {
;         const int col = i * 256 + lane * 4;
;         float4 y;
;         y.x = v[h][i].x * rstd * g4[i].x + b4[i].x;
;         y.y = v[h][i].y * rstd * g4[i].y + b4[i].y;
;         y.z = v[h][i].z * rstd * g4[i].z + b4[i].z;
;         y.w = v[h][i].w * rstd * g4[i].w + b4[i].w;
;         if (l == 1 || rr < MLAT) *(float4*)(p.out + (size_t)rr * 1024 + col) = y;
;         if (l == 0) {
;           const float4 sh = *(const float4*)(md + col), sc = *(const float4*)(md + 1024 + col);
;           uint2 o;
;           o.x = pack2(y.x * (1.f + sc.x) + sh.x, y.y * (1.f + sc.y) + sh.y);
;           o.y = pack2(y.z * (1.f + sc.z) + sh.z, y.w * (1.f + sc.w) + sh.w);
;           *(uint2*)(p.H + (size_t)rr * 1024 + col) = o;
.LBB0_32:
	s_andn2_b64 vcc, exec, s[0:1]
	s_cbranch_vccnz .Lln_nopf
	v_readlane_b32 s98, v255, 30
	v_readlane_b32 s99, v255, 31
	v_lshlrev_b32_e32 v114, 2, v64
	v_mov_b32_e32 v115, v1
	v_min_i32_e32 v116, 0x8000, v62
	v_ashrrev_i32_e32 v116, 11, v116
	v_add_u32_e32 v116, 17, v116
	v_mul_hi_i32_i24_e32 v119, 0x3000, v116
	v_mul_i32_i24_e32 v118, 0x3000, v116
	v_lshl_add_u64 v[118:119], s[98:99], 0, v[118:119]
	v_lshl_add_u64 v[120:121], v[118:119], 0, s[90:91]
	v_lshl_add_u64 v[118:119], v[118:119], 0, v[114:115]
	v_lshl_add_u64 v[120:121], v[120:121], 0, v[114:115]
	global_load_dwordx4 v[128:131], v[120:121], off
	global_load_dwordx4 v[132:135], v[118:119], off
	global_load_dwordx4 v[136:139], v[120:121], off offset:1024
	global_load_dwordx4 v[140:143], v[118:119], off offset:1024
	global_load_dwordx4 v[144:147], v[120:121], off offset:2048
	global_load_dwordx4 v[148:151], v[118:119], off offset:2048
	global_load_dwordx4 v[152:155], v[120:121], off offset:3072
	global_load_dwordx4 v[156:159], v[118:119], off offset:3072
	v_add_u32_e32 v116, 1, v62
	v_min_i32_e32 v116, 0x8000, v116
	v_ashrrev_i32_e32 v116, 11, v116
	v_add_u32_e32 v116, 17, v116
	v_mul_hi_i32_i24_e32 v123, 0x3000, v116
	v_mul_i32_i24_e32 v122, 0x3000, v116
	v_lshl_add_u64 v[122:123], s[98:99], 0, v[122:123]
	v_lshl_add_u64 v[124:125], v[122:123], 0, s[90:91]
	v_lshl_add_u64 v[122:123], v[122:123], 0, v[114:115]
	v_lshl_add_u64 v[124:125], v[124:125], 0, v[114:115]
	global_load_dwordx4 v[160:163], v[124:125], off
	global_load_dwordx4 v[164:167], v[122:123], off
	global_load_dwordx4 v[168:171], v[124:125], off offset:1024
	global_load_dwordx4 v[172:175], v[122:123], off offset:1024
	global_load_dwordx4 v[176:179], v[124:125], off offset:2048
	global_load_dwordx4 v[180:183], v[122:123], off offset:2048
	global_load_dwordx4 v[184:187], v[124:125], off offset:3072
	global_load_dwordx4 v[188:191], v[122:123], off offset:3072

; DI void phase_ln(const P& p, int l) {
;     ...
;       for (int i = 0; i < 4; ++i) {
;         const int col = i * 256 + lane * 4;
;         float4 y;
;         y.x = v[h][i].x * rstd * g4[i].x + b4[i].x;
;         y.y = v[h][i].y * rstd * g4[i].y + b4[i].y;
;         y.z = v[h][i].z * rstd * g4[i].z + b4[i].z;
;         y.w = v[h][i].w * rstd * g4[i].w + b4[i].w;
;         if (l == 1 || rr < MLAT) *(float4*)(p.out + (size_t)rr * 1024 + col) = y;
;         if (l == 0) {
;           const float4 sh = *(const float4*)(md + col), sc = *(const float4*)(md + 1024 + col);
;           uint2 o;
;           o.x = pack2(y.x * (1.f + sc.x) + sh.x, y.y * (1.f + sc.y) + sh.y);
;           o.y = pack2(y.z * (1.f + sc.z) + sh.z, y.w * (1.f + sc.w) + sh.w);
;           *(uint2*)(p.H + (size_t)rr * 1024 + col) = o;
.LBB0_34:
	s_or_b64 exec, exec, s[42:43]
	v_min_i32_e32 v0, 0x8000, v62
	v_ashrrev_i32_e32 v0, 11, v0
	v_add_u32_e32 v0, 17, v0
	v_readlane_b32 s56, v255, 28
	v_mul_hi_i32_i24_e32 v99, 0x3000, v0
	v_mul_i32_i24_e32 v98, 0x3000, v0
	v_readlane_b32 s58, v255, 30
	v_readlane_b32 s59, v255, 31
	v_cndmask_b32_e64 v0, 0, 1, s[0:1]
	v_cmp_ne_u32_e64 s[42:43], 1, v0
	v_lshl_add_u64 v[98:99], s[58:59], 0, v[98:99]
	v_lshl_add_u64 v[100:101], v[98:99], 0, s[90:91]
	s_andn2_b64 vcc, exec, s[0:1]
	v_lshlrev_b32_e32 v0, 2, v64
	v_readlane_b32 s57, v255, 29
	v_readlane_b32 s60, v255, 32
	v_readlane_b32 s61, v255, 33
	v_readlane_b32 s62, v255, 34
	v_readlane_b32 s63, v255, 35
	s_cbranch_vccnz .LBB0_36
	v_lshl_add_u64 v[106:107], v[100:101], 0, v[0:1]
	v_lshl_add_u64 v[110:111], v[98:99], 0, v[0:1]
	v_mov_b32_e32 v106, v128
	v_mov_b32_e32 v107, v129
	v_mov_b32_e32 v108, v130
	v_mov_b32_e32 v109, v131
	v_mov_b32_e32 v110, v132
	v_mov_b32_e32 v111, v133
	v_mov_b32_e32 v112, v134
	v_mov_b32_e32 v113, v135
	v_pk_add_f32 v[106:107], v[106:107], 1.0 op_sel_hi:[1,0]
	v_pk_add_f32 v[108:109], v[108:109], 1.0 op_sel_hi:[1,0]
	v_pk_fma_f32 v[50:51], v[50:51], v[106:107], v[110:111]
	v_pk_fma_f32 v[52:53], v[52:53], v[108:109], v[112:113]
	v_cvt_pk_bf16_f32 v50, v50, v51
	v_cvt_pk_bf16_f32 v51, v52, v53
	global_store_dwordx2 v[84:85], v[50:51], off offset:-1024

; DI void phase_ln(const P& p, int l) {
;     ...
;       for (int i = 0; i < 4; ++i) {
;         const int col = i * 256 + lane * 4;
;         float4 y;
;         y.x = v[h][i].x * rstd * g4[i].x + b4[i].x;
;         y.y = v[h][i].y * rstd * g4[i].y + b4[i].y;
;         y.z = v[h][i].z * rstd * g4[i].z + b4[i].z;
;         y.w = v[h][i].w * rstd * g4[i].w + b4[i].w;
;         if (l == 1 || rr < MLAT) *(float4*)(p.out + (size_t)rr * 1024 + col) = y;
;         if (l == 0) {
;           const float4 sh = *(const float4*)(md + col), sc = *(const float4*)(md + 1024 + col);
;           uint2 o;
;           o.x = pack2(y.x * (1.f + sc.x) + sh.x, y.y * (1.f + sc.y) + sh.y);
;           o.y = pack2(y.z * (1.f + sc.z) + sh.z, y.w * (1.f + sc.w) + sh.w);
;           *(uint2*)(p.H + (size_t)rr * 1024 + col) = o;
.LBB0_38:
	s_or_b64 exec, exec, s[54:55]
	s_and_b64 vcc, exec, s[42:43]
	s_cbranch_vccnz .LBB0_40
	v_lshlrev_b32_e32 v90, 2, v68
	v_mov_b32_e32 v91, v1
	v_lshl_add_u64 v[90:91], v[100:101], 0, v[90:91]
	v_lshl_add_u64 v[106:107], v[98:99], 0, v[0:1]
	v_mov_b32_e32 v90, v136
	v_mov_b32_e32 v91, v137
	v_mov_b32_e32 v92, v138
	v_mov_b32_e32 v93, v139
	v_mov_b32_e32 v106, v140
	v_mov_b32_e32 v107, v141
	v_mov_b32_e32 v108, v142
	v_mov_b32_e32 v109, v143
	v_pk_add_f32 v[90:91], v[90:91], 1.0 op_sel_hi:[1,0]
	v_pk_add_f32 v[92:93], v[92:93], 1.0 op_sel_hi:[1,0]
	v_pk_fma_f32 v[50:51], v[50:51], v[90:91], v[106:107]
	v_pk_fma_f32 v[52:53], v[52:53], v[92:93], v[108:109]
	v_cvt_pk_bf16_f32 v50, v50, v51
	v_cvt_pk_bf16_f32 v51, v52, v53
	global_store_dwordx2 v[84:85], v[50:51], off offset:-512

; DI void phase_ln(const P& p, int l) {
;     ...
;       for (int i = 0; i < 4; ++i) {
;         const int col = i * 256 + lane * 4;
;         float4 y;
;         y.x = v[h][i].x * rstd * g4[i].x + b4[i].x;
;         y.y = v[h][i].y * rstd * g4[i].y + b4[i].y;
;         y.z = v[h][i].z * rstd * g4[i].z + b4[i].z;
;         y.w = v[h][i].w * rstd * g4[i].w + b4[i].w;
;         if (l == 1 || rr < MLAT) *(float4*)(p.out + (size_t)rr * 1024 + col) = y;
;         if (l == 0) {
;           const float4 sh = *(const float4*)(md + col), sc = *(const float4*)(md + 1024 + col);
;           uint2 o;
;           o.x = pack2(y.x * (1.f + sc.x) + sh.x, y.y * (1.f + sc.y) + sh.y);
;           o.y = pack2(y.z * (1.f + sc.z) + sh.z, y.w * (1.f + sc.w) + sh.w);
;           *(uint2*)(p.H + (size_t)rr * 1024 + col) = o;
.LBB0_42:
	s_or_b64 exec, exec, s[54:55]
	s_and_b64 vcc, exec, s[42:43]
	s_cbranch_vccnz .LBB0_44
	v_lshlrev_b32_e32 v58, 2, v70
	v_mov_b32_e32 v59, v1
	v_lshl_add_u64 v[58:59], v[100:101], 0, v[58:59]
	v_lshl_add_u64 v[90:91], v[98:99], 0, v[0:1]
	v_mov_b32_e32 v58, v144
	v_mov_b32_e32 v59, v145
	v_mov_b32_e32 v60, v146
	v_mov_b32_e32 v61, v147
	v_mov_b32_e32 v90, v148
	v_mov_b32_e32 v91, v149
	v_mov_b32_e32 v92, v150
	v_mov_b32_e32 v93, v151
	v_pk_add_f32 v[58:59], v[58:59], 1.0 op_sel_hi:[1,0]
	v_pk_add_f32 v[60:61], v[60:61], 1.0 op_sel_hi:[1,0]
	v_pk_fma_f32 v[50:51], v[50:51], v[58:59], v[90:91]
	v_pk_fma_f32 v[52:53], v[52:53], v[60:61], v[92:93]
	v_cvt_pk_bf16_f32 v50, v50, v51
	v_cvt_pk_bf16_f32 v51, v52, v53
	global_store_dwordx2 v[84:85], v[50:51], off

; DI void phase_ln(const P& p, int l) {
;     ...
;       for (int i = 0; i < 4; ++i) {
;         const int col = i * 256 + lane * 4;
;         float4 y;
;         y.x = v[h][i].x * rstd * g4[i].x + b4[i].x;
;         y.y = v[h][i].y * rstd * g4[i].y + b4[i].y;
;         y.z = v[h][i].z * rstd * g4[i].z + b4[i].z;
;         y.w = v[h][i].w * rstd * g4[i].w + b4[i].w;
;         if (l == 1 || rr < MLAT) *(float4*)(p.out + (size_t)rr * 1024 + col) = y;
;         if (l == 0) {
;           const float4 sh = *(const float4*)(md + col), sc = *(const float4*)(md + 1024 + col);
;           uint2 o;
;           o.x = pack2(y.x * (1.f + sc.x) + sh.x, y.y * (1.f + sc.y) + sh.y);
;           o.y = pack2(y.z * (1.f + sc.z) + sh.z, y.w * (1.f + sc.w) + sh.w);
;           *(uint2*)(p.H + (size_t)rr * 1024 + col) = o;
.LBB0_48:
	v_lshlrev_b32_e32 v54, 2, v72
	v_mov_b32_e32 v55, v1
	v_lshl_add_u64 v[54:55], v[100:101], 0, v[54:55]
	v_lshl_add_u64 v[58:59], v[98:99], 0, v[0:1]
	v_mov_b32_e32 v54, v152
	v_mov_b32_e32 v55, v153
	v_mov_b32_e32 v56, v154
	v_mov_b32_e32 v57, v155
	v_mov_b32_e32 v58, v156
	v_mov_b32_e32 v59, v157
	v_mov_b32_e32 v60, v158
	v_mov_b32_e32 v61, v159
	v_pk_add_f32 v[54:55], v[54:55], 1.0 op_sel_hi:[1,0]
	v_pk_add_f32 v[56:57], v[56:57], 1.0 op_sel_hi:[1,0]
	v_pk_fma_f32 v[50:51], v[50:51], v[54:55], v[58:59]
	v_pk_fma_f32 v[52:53], v[52:53], v[56:57], v[60:61]
	v_cvt_pk_bf16_f32 v50, v50, v51
	v_cvt_pk_bf16_f32 v51, v52, v53
	global_store_dwordx2 v[84:85], v[50:51], off offset:512
	s_and_saveexec_b64 s[52:53], s[40:41]
	s_cbranch_execz .LBB0_31

; DI void phase_ln(const P& p, int l) {
;     ...
;       for (int i = 0; i < 4; ++i) {
;         const int col = i * 256 + lane * 4;
;         float4 y;
;         y.x = v[h][i].x * rstd * g4[i].x + b4[i].x;
;         y.y = v[h][i].y * rstd * g4[i].y + b4[i].y;
;         y.z = v[h][i].z * rstd * g4[i].z + b4[i].z;
;         y.w = v[h][i].w * rstd * g4[i].w + b4[i].w;
;         if (l == 1 || rr < MLAT) *(float4*)(p.out + (size_t)rr * 1024 + col) = y;
;         if (l == 0) {
;           const float4 sh = *(const float4*)(md + col), sc = *(const float4*)(md + 1024 + col);
;           uint2 o;
;           o.x = pack2(y.x * (1.f + sc.x) + sh.x, y.y * (1.f + sc.y) + sh.y);
;           o.y = pack2(y.z * (1.f + sc.z) + sh.z, y.w * (1.f + sc.w) + sh.w);
;           *(uint2*)(p.H + (size_t)rr * 1024 + col) = o;
.LBB0_51:
	s_or_b64 exec, exec, s[54:55]
	v_min_i32_e32 v41, 0x8000, v63
	v_ashrrev_i32_e32 v41, 11, v41
	v_add_u32_e32 v41, 17, v41
	v_readlane_b32 s56, v255, 28
	v_mul_hi_i32_i24_e32 v55, 0x3000, v41
	v_mul_i32_i24_e32 v54, 0x3000, v41
	v_readlane_b32 s58, v255, 30
	v_readlane_b32 s59, v255, 31
	s_and_b64 vcc, exec, s[42:43]
	v_readlane_b32 s57, v255, 29
	v_lshl_add_u64 v[58:59], s[58:59], 0, v[54:55]
	v_lshlrev_b64 v[54:55], 11, v[86:87]
	v_lshl_add_u64 v[56:57], v[58:59], 0, s[90:91]
	v_lshl_add_u64 v[54:55], v[76:77], 0, v[54:55]
	v_readlane_b32 s60, v255, 32
	v_readlane_b32 s61, v255, 33
	v_readlane_b32 s62, v255, 34
	v_readlane_b32 s63, v255, 35
	s_cbranch_vccnz .LBB0_53
	v_lshl_add_u64 v[60:61], v[56:57], 0, v[0:1]
	v_lshl_add_u64 v[60:61], v[58:59], 0, v[0:1]
	v_mov_b32_e32 v86, v160
	v_mov_b32_e32 v87, v161
	v_mov_b32_e32 v88, v162
	v_mov_b32_e32 v89, v163
	v_mov_b32_e32 v90, v164
	v_mov_b32_e32 v91, v165
	v_mov_b32_e32 v92, v166
	v_mov_b32_e32 v93, v167
	v_pk_add_f32 v[60:61], v[86:87], 1.0 op_sel_hi:[1,0]
	v_pk_add_f32 v[86:87], v[88:89], 1.0 op_sel_hi:[1,0]
	v_pk_fma_f32 v[34:35], v[34:35], v[60:61], v[90:91]
	v_pk_fma_f32 v[36:37], v[36:37], v[86:87], v[92:93]
	v_cvt_pk_bf16_f32 v34, v34, v35
	v_cvt_pk_bf16_f32 v35, v36, v37
	global_store_dwordx2 v[54:55], v[34:35], off

; DI void phase_ln(const P& p, int l) {
;     ...
;       for (int i = 0; i < 4; ++i) {
;         const int col = i * 256 + lane * 4;
;         float4 y;
;         y.x = v[h][i].x * rstd * g4[i].x + b4[i].x;
;         y.y = v[h][i].y * rstd * g4[i].y + b4[i].y;
;         y.z = v[h][i].z * rstd * g4[i].z + b4[i].z;
;         y.w = v[h][i].w * rstd * g4[i].w + b4[i].w;
;         if (l == 1 || rr < MLAT) *(float4*)(p.out + (size_t)rr * 1024 + col) = y;
;         if (l == 0) {
;           const float4 sh = *(const float4*)(md + col), sc = *(const float4*)(md + 1024 + col);
;           uint2 o;
;           o.x = pack2(y.x * (1.f + sc.x) + sh.x, y.y * (1.f + sc.y) + sh.y);
;           o.y = pack2(y.z * (1.f + sc.z) + sh.z, y.w * (1.f + sc.w) + sh.w);
;           *(uint2*)(p.H + (size_t)rr * 1024 + col) = o;
.LBB0_55:
	s_or_b64 exec, exec, s[54:55]
	s_and_b64 vcc, exec, s[42:43]
	s_cbranch_vccnz .LBB0_57
	v_lshlrev_b32_e32 v48, 2, v68
	v_mov_b32_e32 v49, v1
	v_lshl_add_u64 v[48:49], v[56:57], 0, v[48:49]
	v_lshl_add_u64 v[60:61], v[58:59], 0, v[0:1]
	v_mov_b32_e32 v48, v168
	v_mov_b32_e32 v49, v169
	v_mov_b32_e32 v50, v170
	v_mov_b32_e32 v51, v171
	v_mov_b32_e32 v86, v172
	v_mov_b32_e32 v87, v173
	v_mov_b32_e32 v88, v174
	v_mov_b32_e32 v89, v175
	v_pk_add_f32 v[48:49], v[48:49], 1.0 op_sel_hi:[1,0]
	v_pk_add_f32 v[50:51], v[50:51], 1.0 op_sel_hi:[1,0]
	v_pk_fma_f32 v[34:35], v[34:35], v[48:49], v[86:87]
	v_pk_fma_f32 v[36:37], v[36:37], v[50:51], v[88:89]
	v_cvt_pk_bf16_f32 v34, v34, v35
	v_cvt_pk_bf16_f32 v35, v36, v37
	global_store_dwordx2 v[54:55], v[34:35], off offset:512

; DI void phase_ln(const P& p, int l) {
;     ...
;       for (int i = 0; i < 4; ++i) {
;         const int col = i * 256 + lane * 4;
;         float4 y;
;         y.x = v[h][i].x * rstd * g4[i].x + b4[i].x;
;         y.y = v[h][i].y * rstd * g4[i].y + b4[i].y;
;         y.z = v[h][i].z * rstd * g4[i].z + b4[i].z;
;         y.w = v[h][i].w * rstd * g4[i].w + b4[i].w;
;         if (l == 1 || rr < MLAT) *(float4*)(p.out + (size_t)rr * 1024 + col) = y;
;         if (l == 0) {
;           const float4 sh = *(const float4*)(md + col), sc = *(const float4*)(md + 1024 + col);
;           uint2 o;
;           o.x = pack2(y.x * (1.f + sc.x) + sh.x, y.y * (1.f + sc.y) + sh.y);
;           o.y = pack2(y.z * (1.f + sc.z) + sh.z, y.w * (1.f + sc.w) + sh.w);
;           *(uint2*)(p.H + (size_t)rr * 1024 + col) = o;
.LBB0_59:
	s_or_b64 exec, exec, s[54:55]
	s_and_b64 vcc, exec, s[42:43]
	s_cbranch_vccnz .LBB0_61
	v_lshlrev_b32_e32 v44, 2, v70
	v_mov_b32_e32 v45, v1
	v_lshl_add_u64 v[44:45], v[56:57], 0, v[44:45]
	v_lshl_add_u64 v[48:49], v[58:59], 0, v[0:1]
	v_mov_b32_e32 v44, v176
	v_mov_b32_e32 v45, v177
	v_mov_b32_e32 v46, v178
	v_mov_b32_e32 v47, v179
	v_mov_b32_e32 v48, v180
	v_mov_b32_e32 v49, v181
	v_mov_b32_e32 v50, v182
	v_mov_b32_e32 v51, v183
	v_pk_add_f32 v[44:45], v[44:45], 1.0 op_sel_hi:[1,0]
	v_pk_add_f32 v[46:47], v[46:47], 1.0 op_sel_hi:[1,0]
	v_pk_fma_f32 v[34:35], v[34:35], v[44:45], v[48:49]
	v_pk_fma_f32 v[36:37], v[36:37], v[46:47], v[50:51]
	v_cvt_pk_bf16_f32 v34, v34, v35
	v_cvt_pk_bf16_f32 v35, v36, v37
	global_store_dwordx2 v[54:55], v[34:35], off offset:1024

; DI void phase_ln(const P& p, int l) {
;     ...
;       for (int i = 0; i < 4; ++i) {
;         const int col = i * 256 + lane * 4;
;         float4 y;
;         y.x = v[h][i].x * rstd * g4[i].x + b4[i].x;
;         y.y = v[h][i].y * rstd * g4[i].y + b4[i].y;
;         y.z = v[h][i].z * rstd * g4[i].z + b4[i].z;
;         y.w = v[h][i].w * rstd * g4[i].w + b4[i].w;
;         if (l == 1 || rr < MLAT) *(float4*)(p.out + (size_t)rr * 1024 + col) = y;
;         if (l == 0) {
;           const float4 sh = *(const float4*)(md + col), sc = *(const float4*)(md + 1024 + col);
;           uint2 o;
;           o.x = pack2(y.x * (1.f + sc.x) + sh.x, y.y * (1.f + sc.y) + sh.y);
;           o.y = pack2(y.z * (1.f + sc.z) + sh.z, y.w * (1.f + sc.w) + sh.w);
;           *(uint2*)(p.H + (size_t)rr * 1024 + col) = o;
.LBB0_63:
	s_or_b64 exec, exec, s[54:55]
	s_and_b64 vcc, exec, s[42:43]
	s_cbranch_vccnz .LBB0_31
	v_lshl_add_u64 v[42:43], v[58:59], 0, v[0:1]
	v_lshlrev_b32_e32 v0, 2, v72
	v_lshl_add_u64 v[38:39], v[56:57], 0, v[0:1]
	s_nop 0
	v_mov_b32_e32 v38, v184
	v_mov_b32_e32 v39, v185
	v_mov_b32_e32 v40, v186
	v_mov_b32_e32 v41, v187
	v_mov_b32_e32 v42, v188
	v_mov_b32_e32 v43, v189
	v_mov_b32_e32 v44, v190
	v_mov_b32_e32 v45, v191
	v_pk_add_f32 v[38:39], v[38:39], 1.0 op_sel_hi:[1,0]
	v_pk_add_f32 v[40:41], v[40:41], 1.0 op_sel_hi:[1,0]
	v_pk_fma_f32 v[34:35], v[34:35], v[38:39], v[42:43]
	v_pk_fma_f32 v[36:37], v[36:37], v[40:41], v[44:45]
	v_cvt_pk_bf16_f32 v34, v34, v35
	v_cvt_pk_bf16_f32 v35, v36, v37
	global_store_dwordx2 v[54:55], v[34:35], off offset:1536
	s_branch .LBB0_31
